# GDN chain waves run at priority 0 instead of 3 (the MLA-side waves sharing their SIMDs are now the longer path of the layer-0 mixer)
# speedup vs baseline: 1.0035x; 1.0035x over previous
; DI void gdn_chain(const P& p, int cid, char* smem) {
;     ...
;   const float Aexp = __expf(p.ev_a_log[dir * 8 + h]);
;   const float dtb = p.ev_dt_bias[dir * 8 + h];
;   __builtin_amdgcn_s_setprio(3);
;   f32x2 S[4];
; #pragma unroll
;   for (int i = 0; i < 4; ++i) S[i] = (f32x2){0.f, 0.f};
;   const int dl = lane & 7, ec = wave * 8 + (lane >> 3);
;   const int pp = tid >> 2, qd = tid & 3;
;   __syncthreads();
.LBB0_946:
	s_or_b64 exec, exec, s[4:5]
	s_ashr_i32 s0, s44, 7
	s_bfe_u32 s1, s44, 0x30004
	s_mul_i32 s5, s0, 0x1200000
	s_mul_hi_i32 s4, s0, 0x1200000
	s_add_u32 s17, s92, s5
	s_addc_u32 s20, s93, s4
	s_lshl_b32 s0, s0, 3
	s_or_b32 s4, s0, s15
	s_ashr_i32 s5, s4, 31
	v_readlane_b32 s72, v223, 38
	s_lshl_b64 s[4:5], s[4:5], 2
	v_readlane_b32 s76, v223, 42
	v_readlane_b32 s77, v223, 43
	s_add_u32 s18, s76, s4
	v_readlane_b32 s78, v223, 44
	s_addc_u32 s19, s77, s5
	v_readlane_b32 s79, v223, 45
	s_add_u32 s4, s78, s4
	global_load_dword v1, v96, s[18:19]
	s_addc_u32 s5, s79, s5
	global_load_dword v49, v96, s[4:5]
	v_readlane_b32 s74, v223, 40
	v_readlane_b32 s75, v223, 41
	v_readlane_b32 s80, v223, 46
	v_readlane_b32 s81, v223, 47
	v_readlane_b32 s82, v223, 48
	v_readlane_b32 s83, v223, 49
	v_readlane_b32 s84, v223, 50
	v_readlane_b32 s85, v223, 51
	v_readlane_b32 s86, v223, 52
	v_readlane_b32 s87, v223, 53
	v_readlane_b32 s73, v223, 39
	s_waitcnt vmcnt(1)
	v_mul_f32_e32 v1, 0x3fb8aa3b, v1
	s_setprio 0
	s_lshl_b32 s46, s1, 8
	s_bitset1_b32 s46, 14
	s_lshl_b32 s47, s1, 11
	s_cmpk_lt_u32 s44, 0x80
	s_cselect_b64 s[74:75], -1, 0
	s_lshl_b32 s1, s16, 1
	v_readlane_b32 s4, v221, 5
	v_readlane_b32 s5, v221, 6
	s_add_u32 s38, s4, s1
	s_addc_u32 s39, s5, 0
	s_add_u32 s1, s17, s1
	s_addc_u32 s5, s20, 0
	s_lshl_b32 s4, s45, 1
	v_ashrrev_i32_e32 v69, 2, v0
	v_and_b32_e32 v3, 3, v0
	s_add_u32 s4, s1, s4
	v_exp_f32_e32 v51, v1
	v_ashrrev_i32_e32 v1, 3, v0
	v_lshrrev_b32_e32 v2, 3, v0
	v_lshlrev_b32_e32 v5, 6, v3
	v_lshl_add_u32 v6, v69, 8, 0
	s_addc_u32 s5, s5, 0
	s_ashr_i32 s1, s0, 31
	v_bfi_b32 v2, -8, v1, v2
	v_add_u32_e32 v70, 0, v5
	v_add_u32_e32 v71, v6, v5
	v_lshlrev_b32_e32 v5, 7, v69
	s_lshl_b64 s[0:1], s[0:1], 2
	v_lshlrev_b32_e32 v48, 4, v3
	v_lshlrev_b32_e32 v50, 3, v3
	v_sub_u32_e32 v5, v6, v5
	v_lshlrev_b32_e32 v6, 5, v3
	v_cmp_eq_u32_e64 s[76:77], 0, v3
	v_ashrrev_i32_e32 v3, 31, v2
	s_add_u32 s0, s36, s0
	v_bfe_u32 v4, v0, 3, 3
	v_lshl_add_u32 v8, v2, 2, 0
	v_lshl_add_u64 v[52:53], v[2:3], 1, s[4:5]
	v_and_b32_e32 v2, 0x3ffffff8, v0
	s_addc_u32 s1, s37, s1
	s_lshl_b32 s4, s15, 2
	v_and_b32_e32 v68, 7, v0
	v_lshl_add_u32 v73, v2, 2, 0
	v_and_b32_e32 v2, 4, v0
	s_add_u32 s40, s0, s4
	v_bitop3_b32 v75, v0, 7, v0 bitop3:0x3f
	v_lshlrev_b32_e32 v0, 2, v1
	v_lshlrev_b32_e32 v1, 2, v4
	s_movk_i32 s0, 0xffe0
	v_and_or_b32 v0, v0, s0, v1
	v_readlane_b32 s0, v218, 42
	v_lshlrev_b32_e32 v7, 5, v68
	v_cmp_ne_u32_e64 s[94:95], 0, v2
	v_sub_u32_e32 v2, 0, v6
	s_addc_u32 s41, s1, 0
	v_add_u32_e32 v76, s0, v0
	s_add_i32 s0, 0, 0x200
	v_mov_b32_e32 v97, v96
	v_add_u32_e32 v72, 0, v7
	v_sub_u32_e32 v74, v70, v6
	v_add_u32_e32 v77, s0, v7
	v_mov_b32_e32 v98, v96
	v_mov_b32_e32 v99, v96
	v_mov_b32_e32 v100, v96
	v_mov_b32_e32 v101, v96
	v_mov_b32_e32 v102, v96
	v_mov_b32_e32 v103, v96
	v_add_u32_e32 v78, v70, v2
	v_add_u32_e32 v79, v5, v6
	v_mov_b64_e32 v[0:1], v[96:97]
	v_cmp_eq_u32_e64 s[78:79], 0, v68
	v_cmp_eq_u32_e64 s[80:81], 1, v68
	v_cmp_eq_u32_e64 s[82:83], 2, v68
	v_cmp_eq_u32_e64 s[84:85], 3, v68
	v_cmp_eq_u32_e64 s[86:87], 4, v68
	v_cmp_eq_u32_e64 s[88:89], 5, v68
	v_cmp_eq_u32_e64 s[90:91], 6, v68
	v_cmp_eq_u32_e64 s[92:93], 7, v68
	s_mov_b64 s[0:1], -1
	v_add_u32_e32 v80, 0x8000, v8
	v_mov_b64_e32 v[2:3], v[98:99]
	v_mov_b64_e32 v[4:5], v[100:101]
	v_mov_b64_e32 v[6:7], v[102:103]
	s_waitcnt lgkmcnt(0)
	s_barrier
